# next-layer weight conversion moved from the scan/attention phase into the w_in GEMM phase (workgroups 320..511 convert after their single tile pair)
# baseline (speedup 1.0000x reference)
.LBB0_231:
	s_cmp_lt_i32 s17, 31
	s_cbranch_scc0 .LBB0_308
	v_readlane_b32 s0, v252, 2
	v_readlane_b32 s1, v252, 3
	s_load_dword s13, s[0:1], 0x0
	s_waitcnt lgkmcnt(0)
	s_cmpk_lt_i32 s13, 0x181
	s_cselect_b64 s[4:5], -1, 0
	s_and_b64 vcc, exec, s[4:5]
	s_cbranch_vccnz .LBB0_234
	s_branch .LBB0_308

.Lg0_exit:
	v_mov_b32_e32 v2, 0x12ff0
	ds_write_b32 v2, v196
	ds_write_b32 v2, v205 offset:4
	s_waitcnt lgkmcnt(0)
	s_cmp_lt_i32 s17, 31
	s_cbranch_scc0 .LBB0_499
	s_cmpk_lt_i32 s2, 0x140
	s_cbranch_scc1 .LBB0_499
	v_readlane_b32 s0, v252, 2
	v_readlane_b32 s1, v252, 3
	s_load_dword s13, s[0:1], 0x0
	s_waitcnt lgkmcnt(0)
	s_cmpk_lt_i32 s13, 0x181
	s_cbranch_scc1 .LBB0_499
	s_mov_b64 s[0:1], 0
	s_nop 0
	v_writelane_b32 v255, s0, 1
	v_writelane_b32 v255, s1, 2
	s_add_i32 s24, s17, -2
	s_mul_hi_u32 s24, s24, 0x1999999a
	s_mov_b64 s[0:1], -1
	s_branch .LBB0_272
